# cache-gather rider: page-table entry fetched with s_load (lgkmcnt) instead of global_load + vmcnt(0) drain; on top of v30
# baseline (speedup 1.0000x reference)
.LBB0_231:
	s_ashr_i32 s3, s2, 13
	s_lshl_b32 s18, s3, 6
	s_bfe_u32 s19, s2, 0x60007
	s_or_b32 s18, s18, s19
	s_ashr_i32 s19, s18, 31
	s_and_b32 s20, s2, 0x1ffe
	s_lshl_b64 s[18:19], s[18:19], 2
	s_add_u32 s18, s12, s18
	s_addc_u32 s19, s13, s19
	s_load_dword s100, s[18:19], 0x0
	s_lshl_b32 s18, s2, 12
	s_and_b32 s40, s18, 0x7e000
	s_or_b32 s18, s20, 1
	s_lshl_b32 s19, s18, 12
	s_lshl_b32 s3, s3, 2
	v_mov_b32_e32 v7, v145
	s_add_i32 s96, s96, s17
	s_add_i32 s2, s2, s91
	s_waitcnt lgkmcnt(0)
	v_mov_b32_e32 v72, s100
	v_ashrrev_i32_e32 v73, 31, v72
	v_lshlrev_b64 v[72:73], 19, v[72:73]
	v_lshl_add_u64 v[88:89], v[4:5], 0, v[72:73]
	v_lshl_add_u64 v[84:85], v[88:89], 0, s[40:41]
	global_load_dwordx4 v[72:75], v[84:85], off nt
	global_load_dwordx4 v[76:79], v[84:85], off offset:1024 nt
	global_load_dwordx4 v[80:83], v[84:85], off offset:2048 nt
	s_nop 0
	global_load_dwordx4 v[84:87], v[84:85], off offset:3072 nt
	s_and_b32 s40, s19, 0x7f000
	v_lshl_add_u64 v[100:101], v[88:89], 0, s[40:41]
	global_load_dwordx4 v[88:91], v[100:101], off nt
	global_load_dwordx4 v[92:95], v[100:101], off offset:1024 nt
	global_load_dwordx4 v[96:99], v[100:101], off offset:2048 nt
	s_nop 0
	global_load_dwordx4 v[100:103], v[100:101], off offset:3072 nt
	s_lshl_b32 s40, s20, 8
	s_waitcnt vmcnt(7)
	v_cvt_pk_bf16_f32 v72, v72, v73
	v_cvt_pk_bf16_f32 v73, v74, v75
	v_or_b32_e32 v74, s3, v3
	v_ashrrev_i32_e32 v75, 31, v74
	v_lshlrev_b64 v[104:105], 21, v[74:75]
	v_or_b32_e32 v74, 2, v74
	v_lshl_add_u64 v[104:105], s[4:5], 0, v[104:105]
	v_ashrrev_i32_e32 v75, 31, v74
	v_lshl_add_u64 v[106:107], v[104:105], 0, s[40:41]
	v_lshlrev_b64 v[74:75], 21, v[74:75]
	v_lshl_add_u64 v[106:107], v[106:107], 0, v[6:7]
	v_lshl_add_u64 v[74:75], s[4:5], 0, v[74:75]
	global_store_dwordx2 v[106:107], v[72:73], off
	s_waitcnt vmcnt(7)
	v_cvt_pk_bf16_f32 v72, v76, v77
	v_lshl_add_u64 v[76:77], v[74:75], 0, s[40:41]
	v_lshl_add_u64 v[76:77], v[76:77], 0, v[6:7]
	v_cvt_pk_bf16_f32 v73, v78, v79
	global_store_dwordx2 v[76:77], v[72:73], off
	v_add_u32_e32 v76, s3, v149
	v_ashrrev_i32_e32 v77, 31, v76
	v_lshlrev_b64 v[76:77], 21, v[76:77]
	v_lshl_add_u64 v[76:77], s[4:5], 0, v[76:77]
	v_lshl_add_u64 v[78:79], v[76:77], 0, s[40:41]
	v_lshl_add_u64 v[78:79], v[78:79], 0, v[6:7]
	s_waitcnt vmcnt(7)
	v_cvt_pk_bf16_f32 v72, v80, v81
	v_cvt_pk_bf16_f32 v73, v82, v83
	global_store_dwordx2 v[78:79], v[72:73], off
	v_add_u32_e32 v78, s3, v156
	v_ashrrev_i32_e32 v79, 31, v78
	v_lshlrev_b64 v[78:79], 21, v[78:79]
	v_lshl_add_u64 v[78:79], s[4:5], 0, v[78:79]
	v_lshl_add_u64 v[80:81], v[78:79], 0, s[40:41]
	v_lshl_add_u64 v[80:81], v[80:81], 0, v[6:7]
	s_lshl_b32 s40, s18, 8
	s_waitcnt vmcnt(7)
	v_cvt_pk_bf16_f32 v72, v84, v85
	v_cvt_pk_bf16_f32 v73, v86, v87
	global_store_dwordx2 v[80:81], v[72:73], off
	v_lshl_add_u64 v[80:81], v[104:105], 0, s[40:41]
	v_lshl_add_u64 v[74:75], v[74:75], 0, s[40:41]
	s_waitcnt vmcnt(7)
	v_cvt_pk_bf16_f32 v72, v88, v89
	v_cvt_pk_bf16_f32 v73, v90, v91
	v_lshl_add_u64 v[80:81], v[80:81], 0, v[6:7]
	v_lshl_add_u64 v[74:75], v[74:75], 0, v[6:7]
	global_store_dwordx2 v[80:81], v[72:73], off
	s_waitcnt vmcnt(7)
	v_cvt_pk_bf16_f32 v72, v92, v93
	v_cvt_pk_bf16_f32 v73, v94, v95
	global_store_dwordx2 v[74:75], v[72:73], off
	v_lshl_add_u64 v[74:75], v[76:77], 0, s[40:41]
	v_lshl_add_u64 v[74:75], v[74:75], 0, v[6:7]
	s_waitcnt vmcnt(7)
	v_cvt_pk_bf16_f32 v72, v96, v97
	v_cvt_pk_bf16_f32 v73, v98, v99
	global_store_dwordx2 v[74:75], v[72:73], off
	v_lshl_add_u64 v[74:75], v[78:79], 0, s[40:41]
	v_lshl_add_u64 v[74:75], v[74:75], 0, v[6:7]
	s_cmp_ge_i32 s96, s93
	s_waitcnt vmcnt(7)
	v_cvt_pk_bf16_f32 v72, v100, v101
	v_cvt_pk_bf16_f32 v73, v102, v103
	global_store_dwordx2 v[74:75], v[72:73], off
	s_cbranch_scc0 .LBB0_231
	s_branch .LBB0_179

.LBB0_265:
	s_andn2_b64 vcc, exec, s[68:69]
	s_cbranch_vccnz .LBB0_239
	s_lshl_b32 s18, s78, 1
	s_add_i32 s22, s18, 0xfffe59e0
	s_ashr_i32 s23, s22, 13
	s_lshl_b32 s18, s23, 6
	s_bfe_u32 s19, s22, 0x60007
	s_or_b32 s18, s18, s19
	s_ashr_i32 s19, s18, 31
	s_and_b32 s36, s22, 0x1ffe
	s_lshl_b64 s[18:19], s[18:19], 2
	s_add_u32 s18, s12, s18
	s_addc_u32 s19, s13, s19
	s_load_dword s100, s[18:19], 0x0
	s_lshl_b32 s18, s22, 12
	s_and_b32 s40, s18, 0x7e000
	s_or_b32 s18, s36, 1
	s_lshl_b32 s19, s18, 12
	v_mov_b32_e32 v79, v145
	s_waitcnt lgkmcnt(0)
	v_mov_b32_e32 v0, s100
	v_ashrrev_i32_e32 v1, 31, v0
	v_lshlrev_b64 v[0:1], 19, v[0:1]
	v_lshl_add_u64 v[0:1], v[76:77], 0, v[0:1]
	v_lshl_add_u64 v[2:3], v[0:1], 0, s[40:41]
	global_load_dwordx4 v[16:19], v[2:3], off nt
	global_load_dwordx4 v[20:23], v[2:3], off offset:1024 nt
	global_load_dwordx4 v[24:27], v[2:3], off offset:2048 nt
	global_load_dwordx4 v[28:31], v[2:3], off offset:3072 nt
	s_and_b32 s40, s19, 0x7f000
	v_lshl_add_u64 v[0:1], v[0:1], 0, s[40:41]
	global_load_dwordx4 v[12:15], v[0:1], off nt
	global_load_dwordx4 v[8:11], v[0:1], off offset:1024 nt
	global_load_dwordx4 v[4:7], v[0:1], off offset:2048 nt
	s_nop 0
	global_load_dwordx4 v[0:3], v[0:1], off offset:3072 nt
	s_lshl_b32 s19, s23, 2
	s_lshl_b32 s40, s36, 8
	s_waitcnt vmcnt(7)
	v_cvt_pk_bf16_f32 v32, v16, v17
	v_cvt_pk_bf16_f32 v33, v18, v19
	v_or_b32_e32 v18, s19, v69
	v_ashrrev_i32_e32 v19, 31, v18
	v_lshlrev_b64 v[16:17], 21, v[18:19]
	v_or_b32_e32 v18, 2, v18
	v_lshl_add_u64 v[16:17], s[46:47], 0, v[16:17]
	v_ashrrev_i32_e32 v19, 31, v18
	v_lshl_add_u64 v[34:35], v[16:17], 0, s[40:41]
	v_lshlrev_b64 v[18:19], 21, v[18:19]
	v_lshl_add_u64 v[34:35], v[34:35], 0, v[78:79]
	v_lshl_add_u64 v[18:19], s[46:47], 0, v[18:19]
	global_store_dwordx2 v[34:35], v[32:33], off
	s_waitcnt vmcnt(7)
	v_cvt_pk_bf16_f32 v20, v20, v21
	v_cvt_pk_bf16_f32 v21, v22, v23
	v_lshl_add_u64 v[22:23], v[18:19], 0, s[40:41]
	v_lshl_add_u64 v[22:23], v[22:23], 0, v[78:79]
	global_store_dwordx2 v[22:23], v[20:21], off
	v_add_u32_e32 v22, s19, v164
	v_ashrrev_i32_e32 v23, 31, v22
	v_lshlrev_b64 v[22:23], 21, v[22:23]
	v_lshl_add_u64 v[22:23], s[46:47], 0, v[22:23]
	s_waitcnt vmcnt(7)
	v_cvt_pk_bf16_f32 v20, v24, v25
	v_lshl_add_u64 v[24:25], v[22:23], 0, s[40:41]
	v_lshl_add_u64 v[24:25], v[24:25], 0, v[78:79]
	v_cvt_pk_bf16_f32 v21, v26, v27
	global_store_dwordx2 v[24:25], v[20:21], off
	v_add_u32_e32 v24, s19, v165
	v_ashrrev_i32_e32 v25, 31, v24
	v_lshlrev_b64 v[24:25], 21, v[24:25]
	v_lshl_add_u64 v[24:25], s[46:47], 0, v[24:25]
	v_lshl_add_u64 v[26:27], v[24:25], 0, s[40:41]
	v_lshl_add_u64 v[26:27], v[26:27], 0, v[78:79]
	s_lshl_b32 s40, s18, 8
	s_waitcnt vmcnt(7)
	v_cvt_pk_bf16_f32 v20, v28, v29
	v_cvt_pk_bf16_f32 v21, v30, v31
	global_store_dwordx2 v[26:27], v[20:21], off
	s_waitcnt vmcnt(7)
	v_cvt_pk_bf16_f32 v12, v12, v13
	v_cvt_pk_bf16_f32 v13, v14, v15
	v_lshl_add_u64 v[14:15], v[16:17], 0, s[40:41]
	v_lshl_add_u64 v[14:15], v[14:15], 0, v[78:79]
	global_store_dwordx2 v[14:15], v[12:13], off
	s_waitcnt vmcnt(7)
	v_cvt_pk_bf16_f32 v8, v8, v9
	v_cvt_pk_bf16_f32 v9, v10, v11
	v_lshl_add_u64 v[10:11], v[18:19], 0, s[40:41]
	v_lshl_add_u64 v[10:11], v[10:11], 0, v[78:79]
	global_store_dwordx2 v[10:11], v[8:9], off
	s_waitcnt vmcnt(7)
	v_cvt_pk_bf16_f32 v4, v4, v5
	v_cvt_pk_bf16_f32 v5, v6, v7
	v_lshl_add_u64 v[6:7], v[22:23], 0, s[40:41]
	v_lshl_add_u64 v[6:7], v[6:7], 0, v[78:79]
	global_store_dwordx2 v[6:7], v[4:5], off
	s_waitcnt vmcnt(7)
	v_cvt_pk_bf16_f32 v0, v0, v1
	v_cvt_pk_bf16_f32 v1, v2, v3
	v_lshl_add_u64 v[2:3], v[24:25], 0, s[40:41]
	v_lshl_add_u64 v[2:3], v[2:3], 0, v[78:79]
	global_store_dwordx2 v[2:3], v[0:1], off
	s_branch .LBB0_239
